# norm2 phase: row loads hoisted above the modulation-vector reload, reload's 12 loads issued together (was 4 serialized load/wait groups)
# baseline (speedup 1.0000x reference)
.LBB0_699:
	s_or_b64 exec, exec, s[34:35]
	s_mov_b32 s10, 0x358637bd
	s_mov_b32 s5, 0xed0ff000
	v_add_u32_e32 v34, s26, v34
	s_waitcnt vmcnt(0)
	v_lshlrev_b32_e32 v79, 16, v68
	v_and_b32_e32 v113, 0xffff0000, v70
	v_and_b32_e32 v115, 0xffff0000, v71
	v_lshlrev_b32_e32 v112, 16, v70
	v_lshlrev_b32_e32 v114, 16, v71
	v_lshlrev_b32_e32 v53, 16, v60
	v_and_b32_e32 v51, 0xffff0000, v60
	v_and_b32_e32 v109, 0xffff0000, v73
	v_and_b32_e32 v108, 0xffff0000, v72
	v_mul_f32_e32 v50, v115, v115
	v_mul_f32_e32 v52, v113, v113
	v_and_b32_e32 v77, 0xffff0000, v68
	v_lshlrev_b32_e32 v74, 16, v69
	v_and_b32_e32 v75, 0xffff0000, v69
	v_lshlrev_b32_e32 v111, 16, v73
	v_lshlrev_b32_e32 v110, 16, v72
	v_and_b32_e32 v101, 0xffff0000, v86
	v_and_b32_e32 v105, 0xffff0000, v87
	v_lshlrev_b32_e32 v73, 16, v95
	v_lshlrev_b32_e32 v72, 16, v94
	v_and_b32_e32 v69, 0xffff0000, v95
	v_and_b32_e32 v68, 0xffff0000, v94
	v_pk_mul_f32 v[94:95], v[108:109], v[108:109]
	v_pk_fma_f32 v[106:107], v[114:115], v[114:115], v[50:51] op_sel_hi:[1,1,0]
	v_pk_fma_f32 v[116:117], v[112:113], v[112:113], v[52:53] op_sel_hi:[1,1,0]
	v_lshlrev_b32_e32 v59, 16, v48
	v_and_b32_e32 v57, 0xffff0000, v48
	v_lshlrev_b32_e32 v100, 16, v86
	v_lshlrev_b32_e32 v104, 16, v87
	v_mov_b32_e32 v99, v79
	v_mul_f32_e32 v56, v101, v101
	v_mul_f32_e32 v58, v105, v105
	v_pk_fma_f32 v[94:95], v[110:111], v[110:111], v[94:95]
	v_mov_b32_e32 v78, v116
	v_mov_b32_e32 v98, v106
	v_mul_f32_e32 v35, v77, v77
	v_mul_f32_e32 v41, v74, v74
	v_mul_f32_e32 v43, v75, v75
	v_pk_fma_f32 v[120:121], v[100:101], v[100:101], v[56:57] op_sel_hi:[1,1,0]
	v_pk_fma_f32 v[128:129], v[104:105], v[104:105], v[58:59] op_sel_hi:[1,1,0]
	v_pk_add_f32 v[106:107], v[116:117], v[106:107]
	v_pk_add_f32 v[94:95], v[94:95], v[94:95] op_sel:[0,1] op_sel_hi:[1,0]
	v_pk_mul_f32 v[98:99], v[78:79], v[98:99]
	v_lshlrev_b32_e32 v86, 16, v92
	v_and_b32_e32 v87, 0xffff0000, v92
	v_lshlrev_b32_e32 v92, 16, v93
	v_and_b32_e32 v93, 0xffff0000, v93
	v_mov_b32_e32 v121, v41
	v_mov_b32_e32 v129, v43
	v_mov_b32_e32 v95, v35
	v_mov_b32_e32 v107, v99
	v_and_b32_e32 v63, 0xffff0000, v66
	v_mul_f32_e32 v62, v93, v93
	v_pk_add_f32 v[116:117], v[120:121], v[128:129]
	v_pk_add_f32 v[94:95], v[106:107], v[94:95]
	v_mul_f32_e32 v50, v87, v87
	v_lshlrev_b32_e32 v65, 16, v66
	v_pk_fma_f32 v[130:131], v[92:93], v[92:93], v[62:63] op_sel_hi:[1,1,0]
	v_pk_add_f32 v[116:117], v[94:95], v[116:117]
	v_pk_fma_f32 v[94:95], v[86:87], v[86:87], v[50:51] op_sel_hi:[1,1,0]
	v_lshlrev_b32_e32 v54, 16, v49
	v_and_b32_e32 v55, 0xffff0000, v49
	v_lshlrev_b32_e32 v48, 16, v61
	v_and_b32_e32 v49, 0xffff0000, v61
	v_lshlrev_b32_e32 v60, 16, v67
	v_and_b32_e32 v61, 0xffff0000, v67
	v_lshlrev_b32_e32 v66, 16, v96
	v_and_b32_e32 v67, 0xffff0000, v96
	v_lshlrev_b32_e32 v70, 16, v97
	v_pk_mul_f32 v[102:103], v[68:69], v[68:69]
	v_and_b32_e32 v71, 0xffff0000, v97
	v_mov_b32_e32 v64, v94
	v_mov_b32_e32 v96, v130
	v_mov_b32_e32 v97, v65
	v_pk_fma_f32 v[102:103], v[72:73], v[72:73], v[102:103]
	v_pk_add_f32 v[94:95], v[94:95], v[130:131]
	v_pk_mul_f32 v[96:97], v[64:65], v[96:97]
	v_mul_f32_e32 v35, v63, v63
	v_mov_b32_e32 v95, v97
	v_pk_add_f32 v[96:97], v[102:103], v[102:103] op_sel:[0,1] op_sel_hi:[1,0]
	v_mul_f32_e32 v50, v67, v67
	v_mov_b32_e32 v97, v35
	v_pk_add_f32 v[94:95], v[94:95], v[96:97]
	v_pk_fma_f32 v[96:97], v[66:67], v[66:67], v[50:51] op_sel_hi:[1,1,0]
	v_mul_f32_e32 v50, v71, v71
	v_mul_f32_e32 v41, v60, v60
	v_mul_f32_e32 v43, v61, v61
	v_pk_fma_f32 v[98:99], v[70:71], v[70:71], v[50:51] op_sel_hi:[1,1,0]
	v_mov_b32_e32 v97, v41
	v_mov_b32_e32 v99, v43
	v_pk_add_f32 v[96:97], v[96:97], v[98:99]
	v_mov_b32_e32 v135, v116
	v_pk_add_f32 v[128:129], v[94:95], v[96:97]
	v_and_b32_e32 v107, 0xffff0000, v91
	v_mov_b32_e32 v134, v128
	v_mov_b32_e32 v116, v129
	v_pk_add_f32 v[128:129], v[134:135], v[116:117]
	ds_bpermute_b32 v135, v122, v129
	ds_bpermute_b32 v134, v122, v128
	v_and_b32_e32 v103, 0xffff0000, v90
	v_lshlrev_b32_e32 v106, 16, v91
	v_mul_f32_e32 v50, v107, v107
	v_and_b32_e32 v97, 0xffff0000, v89
	s_waitcnt lgkmcnt(0)
	v_pk_add_f32 v[128:129], v[128:129], v[134:135]
	ds_bpermute_b32 v135, v123, v129
	ds_bpermute_b32 v134, v123, v128
	v_and_b32_e32 v96, 0xffff0000, v88
	v_lshlrev_b32_e32 v102, 16, v90
	v_pk_fma_f32 v[90:91], v[106:107], v[106:107], v[50:51] op_sel_hi:[1,1,0]
	v_lshlrev_b32_e32 v99, 16, v89
	s_waitcnt lgkmcnt(0)
	v_pk_add_f32 v[128:129], v[128:129], v[134:135]
	ds_bpermute_b32 v135, v124, v129
	ds_bpermute_b32 v134, v124, v128
	v_lshlrev_b32_e32 v98, 16, v88
	v_pk_mul_f32 v[88:89], v[96:97], v[96:97]
	v_mul_f32_e32 v50, v103, v103
	v_pk_fma_f32 v[120:121], v[98:99], v[98:99], v[88:89]
	v_lshlrev_b32_e32 v88, 16, v84
	v_and_b32_e32 v89, 0xffff0000, v84
	v_lshlrev_b32_e32 v94, 16, v85
	v_and_b32_e32 v95, 0xffff0000, v85
	v_pk_fma_f32 v[84:85], v[102:103], v[102:103], v[50:51] op_sel_hi:[1,1,0]
	v_mov_b32_e32 v130, v90
	v_mov_b32_e32 v58, v84
	v_mov_b32_e32 v131, v59
	v_pk_add_f32 v[84:85], v[84:85], v[90:91]
	v_pk_mul_f32 v[90:91], v[58:59], v[130:131]
	v_mul_f32_e32 v35, v57, v57
	v_mov_b32_e32 v85, v91
	v_pk_add_f32 v[90:91], v[120:121], v[120:121] op_sel:[0,1] op_sel_hi:[1,0]
	s_waitcnt lgkmcnt(0)
	v_pk_add_f32 v[128:129], v[128:129], v[134:135]
	v_mov_b32_e32 v91, v35
	v_mul_f32_e32 v50, v89, v89
	ds_bpermute_b32 v135, v125, v129
	ds_bpermute_b32 v134, v125, v128
	v_pk_add_f32 v[84:85], v[84:85], v[90:91]
	v_pk_fma_f32 v[90:91], v[88:89], v[88:89], v[50:51] op_sel_hi:[1,1,0]
	v_mul_f32_e32 v50, v95, v95
	v_mul_f32_e32 v41, v54, v54
	v_mul_f32_e32 v43, v55, v55
	v_pk_fma_f32 v[120:121], v[94:95], v[94:95], v[50:51] op_sel_hi:[1,1,0]
	v_mov_b32_e32 v91, v41
	v_mov_b32_e32 v121, v43
	v_pk_add_f32 v[90:91], v[90:91], v[120:121]
	s_waitcnt lgkmcnt(0)
	v_pk_add_f32 v[128:129], v[128:129], v[134:135]
	v_pk_add_f32 v[120:121], v[84:85], v[90:91]
	v_and_b32_e32 v91, 0xffff0000, v83
	v_and_b32_e32 v85, 0xffff0000, v82
	v_lshlrev_b32_e32 v90, 16, v83
	v_mul_f32_e32 v50, v91, v91
	ds_bpermute_b32 v135, v126, v129
	ds_bpermute_b32 v134, v126, v128
	v_lshlrev_b32_e32 v84, 16, v82
	v_pk_fma_f32 v[130:131], v[90:91], v[90:91], v[50:51] op_sel_hi:[1,1,0]
	v_lshlrev_b32_e32 v83, 16, v81
	v_lshlrev_b32_e32 v82, 16, v80
	v_and_b32_e32 v81, 0xffff0000, v81
	v_and_b32_e32 v80, 0xffff0000, v80
	v_mul_f32_e32 v50, v85, v85
	v_pk_mul_f32 v[132:133], v[80:81], v[80:81]
	v_pk_fma_f32 v[136:137], v[84:85], v[84:85], v[50:51] op_sel_hi:[1,1,0]
	v_pk_fma_f32 v[132:133], v[82:83], v[82:83], v[132:133]
	v_mov_b32_e32 v52, v136
	v_mov_b32_e32 v138, v130
	v_mov_b32_e32 v139, v53
	v_mul_f32_e32 v35, v51, v51
	v_pk_add_f32 v[130:131], v[136:137], v[130:131]
	v_pk_mul_f32 v[136:137], v[52:53], v[138:139]
	v_pk_add_f32 v[132:133], v[132:133], v[132:133] op_sel:[0,1] op_sel_hi:[1,0]
	v_mov_b32_e32 v131, v137
	v_mov_b32_e32 v133, v35
	s_waitcnt lgkmcnt(0)
	v_pk_add_f32 v[128:129], v[128:129], v[134:135]
	v_pk_add_f32 v[130:131], v[130:131], v[132:133]
	ds_bpermute_b32 v133, v127, v129
	ds_bpermute_b32 v132, v127, v128
	v_and_b32_e32 v117, 0xffff0000, v118
	v_lshlrev_b32_e32 v116, 16, v118
	v_mul_f32_e32 v50, v117, v117
	v_lshlrev_b32_e32 v118, 16, v119
	s_waitcnt lgkmcnt(0)
	v_pk_add_f32 v[128:129], v[128:129], v[132:133]
	v_mov_b64_e32 v[132:133], s[10:11]
	v_pk_fma_f32 v[128:129], v[128:129], s[82:83], v[132:133] op_sel_hi:[1,0,0]
	v_and_b32_e32 v119, 0xffff0000, v119
	v_mul_f32_e32 v35, 0x4b800000, v129
	v_cmp_gt_f32_e32 vcc, s3, v129
	v_mul_f32_e32 v41, v48, v48
	v_pk_fma_f32 v[134:135], v[116:117], v[116:117], v[50:51] op_sel_hi:[1,1,0]
	v_cndmask_b32_e32 v35, v129, v35, vcc
	v_rsq_f32_e32 v35, v35
	v_mov_b32_e32 v135, v41
	v_mul_f32_e32 v50, v119, v119
	v_pk_fma_f32 v[136:137], v[118:119], v[118:119], v[50:51] op_sel_hi:[1,1,0]
	v_mul_f32_e32 v41, 0x45800000, v35
	v_cndmask_b32_e32 v50, v35, v41, vcc
	v_pk_mul_f32 v[112:113], v[50:51], v[112:113] op_sel_hi:[0,1]
	v_pk_mul_f32 v[114:115], v[50:51], v[114:115] op_sel_hi:[0,1]
	v_pk_fma_f32 v[114:115], v[4:5], v[114:115], v[8:9]
	v_pk_fma_f32 v[112:113], v[2:3], v[112:113], v[6:7]
	v_mul_f32_e32 v35, 0x4b800000, v128
	v_cvt_pk_bf16_f32 v112, v112, v113
	v_cvt_pk_bf16_f32 v113, v114, v115
	v_add_co_u32_e32 v114, vcc, s5, v38
	v_mov_b32_e32 v76, v79
	s_nop 0
	v_addc_co_u32_e32 v115, vcc, -1, v39, vcc
	v_cmp_gt_f32_e32 vcc, s3, v128
	global_store_dwordx2 v[114:115], v[112:113], off offset:-3584
	v_mov_b32_e32 v112, v110
	v_cndmask_b32_e32 v35, v128, v35, vcc
	v_rsq_f32_e32 v35, v35
	v_mov_b32_e32 v113, v108
	v_pk_mul_f32 v[112:113], v[50:51], v[112:113] op_sel_hi:[0,1]
	v_mov_b32_e32 v108, v111
	v_pk_mul_f32 v[100:101], v[50:51], v[100:101] op_sel_hi:[0,1]
	v_pk_mul_f32 v[76:77], v[50:51], v[76:77] op_sel_hi:[0,1]
	v_pk_mul_f32 v[74:75], v[50:51], v[74:75] op_sel_hi:[0,1]
	v_mul_f32_e32 v41, 0x45800000, v35
	v_mul_f32_e32 v43, v49, v49
	v_pk_mul_f32 v[108:109], v[50:51], v[108:109] op_sel_hi:[0,1]
	v_pk_fma_f32 v[110:111], v[10:11], v[112:113], v[14:15]
	v_pk_mul_f32 v[104:105], v[50:51], v[104:105] op_sel_hi:[0,1]
	v_pk_fma_f32 v[100:101], v[18:19], v[100:101], v[22:23]
	v_pk_fma_f32 v[74:75], v[32:33], v[74:75], v[28:29]
	v_pk_fma_f32 v[76:77], v[30:31], v[76:77], v[26:27]
	v_cndmask_b32_e32 v50, v35, v41, vcc
	v_mov_b32_e32 v137, v43
	v_pk_fma_f32 v[108:109], v[12:13], v[108:109], v[16:17]
	v_cvt_pk_bf16_f32 v110, v110, v111
	v_pk_fma_f32 v[104:105], v[20:21], v[104:105], v[24:25]
	v_cvt_pk_bf16_f32 v111, v108, v109
	global_store_dwordx2 v[114:115], v[110:111], off offset:-3072
	v_cvt_pk_bf16_f32 v100, v100, v101
	v_cvt_pk_bf16_f32 v101, v104, v105
	global_store_dwordx2 v[114:115], v[100:101], off offset:-2560
	v_cvt_pk_bf16_f32 v76, v76, v77
	v_cvt_pk_bf16_f32 v77, v74, v75
	v_pk_mul_f32 v[74:75], v[50:51], v[86:87] op_sel_hi:[0,1]
	v_pk_add_f32 v[134:135], v[134:135], v[136:137]
	global_store_dwordx2 v[114:115], v[76:77], off offset:-2048
	v_pk_mul_f32 v[76:77], v[50:51], v[92:93] op_sel_hi:[0,1]
	v_pk_fma_f32 v[74:75], v[2:3], v[74:75], v[6:7]
	v_pk_add_f32 v[130:131], v[130:131], v[134:135]
	v_pk_fma_f32 v[76:77], v[4:5], v[76:77], v[8:9]
	v_cvt_pk_bf16_f32 v74, v74, v75
	v_mov_b32_e32 v78, v72
	v_cvt_pk_bf16_f32 v75, v76, v77
	global_store_dwordx2 v[114:115], v[74:75], off offset:-1536
	v_mov_b32_e32 v74, v130
	v_mov_b32_e32 v75, v120
	v_mov_b32_e32 v120, v131
	v_pk_add_f32 v[74:75], v[74:75], v[120:121]
	ds_bpermute_b32 v77, v122, v75
	ds_bpermute_b32 v76, v122, v74
	v_mov_b32_e32 v79, v68
	v_mov_b32_e32 v68, v73
	v_pk_mul_f32 v[78:79], v[50:51], v[78:79] op_sel_hi:[0,1]
	v_pk_mul_f32 v[68:69], v[50:51], v[68:69] op_sel_hi:[0,1]
	s_waitcnt lgkmcnt(0)
	v_pk_add_f32 v[72:73], v[74:75], v[76:77]
	ds_bpermute_b32 v75, v123, v73
	ds_bpermute_b32 v74, v123, v72
	v_pk_fma_f32 v[68:69], v[12:13], v[68:69], v[16:17]
	v_pk_fma_f32 v[76:77], v[10:11], v[78:79], v[14:15]
	v_pk_mul_f32 v[66:67], v[50:51], v[66:67] op_sel_hi:[0,1]
	v_cvt_pk_bf16_f32 v76, v76, v77
	s_waitcnt lgkmcnt(0)
	v_pk_add_f32 v[72:73], v[72:73], v[74:75]
	ds_bpermute_b32 v75, v124, v73
	ds_bpermute_b32 v74, v124, v72
	v_cvt_pk_bf16_f32 v77, v68, v69
	v_pk_mul_f32 v[68:69], v[50:51], v[70:71] op_sel_hi:[0,1]
	v_pk_fma_f32 v[68:69], v[20:21], v[68:69], v[24:25]
	v_pk_fma_f32 v[66:67], v[18:19], v[66:67], v[22:23]
	s_waitcnt lgkmcnt(0)
	v_pk_add_f32 v[70:71], v[72:73], v[74:75]
	ds_bpermute_b32 v73, v125, v71
	ds_bpermute_b32 v72, v125, v70
	global_store_dwordx2 v[114:115], v[76:77], off offset:-1024
	v_cvt_pk_bf16_f32 v66, v66, v67
	v_cvt_pk_bf16_f32 v67, v68, v69
	v_mov_b32_e32 v62, v65
	s_waitcnt lgkmcnt(0)
	v_pk_add_f32 v[68:69], v[70:71], v[72:73]
	ds_bpermute_b32 v71, v126, v69
	ds_bpermute_b32 v70, v126, v68
	global_store_dwordx2 v[114:115], v[66:67], off offset:-512
	v_pk_mul_f32 v[62:63], v[50:51], v[62:63] op_sel_hi:[0,1]
	v_pk_mul_f32 v[60:61], v[50:51], v[60:61] op_sel_hi:[0,1]
	v_pk_fma_f32 v[60:61], v[32:33], v[60:61], v[28:29]
	s_waitcnt lgkmcnt(0)
	v_pk_add_f32 v[64:65], v[68:69], v[70:71]
	ds_bpermute_b32 v67, v127, v65
	ds_bpermute_b32 v66, v127, v64
	v_pk_fma_f32 v[62:63], v[30:31], v[62:63], v[26:27]
	s_mov_b32 s5, 0xed100000
	v_cvt_pk_bf16_f32 v62, v62, v63
	v_cvt_pk_bf16_f32 v63, v60, v61
	s_waitcnt lgkmcnt(0)
	v_pk_add_f32 v[60:61], v[64:65], v[66:67]
	v_add_co_u32_e64 v64, s[36:37], s5, v38
	v_pk_fma_f32 v[60:61], v[60:61], s[82:83], v[132:133] op_sel_hi:[1,0,0]
	s_nop 0
	v_addc_co_u32_e64 v65, s[36:37], -1, v39, s[36:37]
	v_mul_f32_e32 v35, 0x4b800000, v61
	v_cmp_gt_f32_e32 vcc, s3, v61
	global_store_dwordx2 v[64:65], v[62:63], off offset:-4096
	v_mov_b32_e32 v56, v59
	v_cndmask_b32_e32 v35, v61, v35, vcc
	v_rsq_f32_e32 v35, v35
	v_lshl_add_u64 v[38:39], v[38:39], 0, s[28:29]
	v_mul_f32_e32 v41, 0x45800000, v35
	v_cndmask_b32_e32 v50, v35, v41, vcc
	v_pk_mul_f32 v[62:63], v[50:51], v[102:103] op_sel_hi:[0,1]
	v_pk_mul_f32 v[66:67], v[50:51], v[106:107] op_sel_hi:[0,1]
	v_pk_fma_f32 v[62:63], v[2:3], v[62:63], v[6:7]
	v_mul_f32_e32 v35, 0x4b800000, v60
	v_cmp_gt_f32_e32 vcc, s3, v60
	v_pk_fma_f32 v[66:67], v[4:5], v[66:67], v[8:9]
	v_cvt_pk_bf16_f32 v62, v62, v63
	v_pk_mul_f32 v[56:57], v[50:51], v[56:57] op_sel_hi:[0,1]
	v_cvt_pk_bf16_f32 v63, v66, v67
	v_cndmask_b32_e32 v35, v60, v35, vcc
	global_store_dwordx2 v[64:65], v[62:63], off offset:-3584
	v_mov_b32_e32 v62, v98
	v_mov_b32_e32 v63, v96
	v_rsq_f32_e32 v35, v35
	v_pk_mul_f32 v[62:63], v[50:51], v[62:63] op_sel_hi:[0,1]
	v_mov_b32_e32 v96, v99
	v_pk_mul_f32 v[66:67], v[50:51], v[96:97] op_sel_hi:[0,1]
	v_pk_fma_f32 v[62:63], v[10:11], v[62:63], v[14:15]
	v_pk_fma_f32 v[66:67], v[12:13], v[66:67], v[16:17]
	v_cvt_pk_bf16_f32 v62, v62, v63
	v_pk_mul_f32 v[54:55], v[50:51], v[54:55] op_sel_hi:[0,1]
	v_cvt_pk_bf16_f32 v63, v66, v67
	global_store_dwordx2 v[64:65], v[62:63], off offset:-3072
	v_pk_mul_f32 v[62:63], v[50:51], v[88:89] op_sel_hi:[0,1]
	v_mul_f32_e32 v41, 0x45800000, v35
	v_pk_mul_f32 v[66:67], v[50:51], v[94:95] op_sel_hi:[0,1]
	v_pk_fma_f32 v[62:63], v[18:19], v[62:63], v[22:23]
	v_pk_fma_f32 v[54:55], v[32:33], v[54:55], v[28:29]
	v_pk_fma_f32 v[56:57], v[30:31], v[56:57], v[26:27]
	v_cndmask_b32_e32 v52, v35, v41, vcc
	v_pk_fma_f32 v[66:67], v[20:21], v[66:67], v[24:25]
	v_cvt_pk_bf16_f32 v62, v62, v63
	v_mov_b32_e32 v50, v53
	v_cvt_pk_bf16_f32 v63, v66, v67
	global_store_dwordx2 v[64:65], v[62:63], off offset:-2560
	v_cvt_pk_bf16_f32 v56, v56, v57
	v_cvt_pk_bf16_f32 v57, v54, v55
	v_pk_mul_f32 v[54:55], v[52:53], v[84:85] op_sel_hi:[0,1]
	global_store_dwordx2 v[64:65], v[56:57], off offset:-2048
	v_pk_mul_f32 v[56:57], v[52:53], v[90:91] op_sel_hi:[0,1]
	v_pk_fma_f32 v[54:55], v[2:3], v[54:55], v[6:7]
	v_pk_fma_f32 v[56:57], v[4:5], v[56:57], v[8:9]
	v_cvt_pk_bf16_f32 v54, v54, v55
	v_pk_mul_f32 v[50:51], v[52:53], v[50:51] op_sel_hi:[0,1]
	v_cvt_pk_bf16_f32 v55, v56, v57
	global_store_dwordx2 v[64:65], v[54:55], off offset:-1536
	v_mov_b32_e32 v54, v82
	v_mov_b32_e32 v55, v80
	v_pk_mul_f32 v[54:55], v[52:53], v[54:55] op_sel_hi:[0,1]
	v_mov_b32_e32 v80, v83
	v_pk_mul_f32 v[56:57], v[52:53], v[80:81] op_sel_hi:[0,1]
	v_pk_fma_f32 v[54:55], v[10:11], v[54:55], v[14:15]
	v_pk_fma_f32 v[56:57], v[12:13], v[56:57], v[16:17]
	v_cvt_pk_bf16_f32 v54, v54, v55
	v_cmp_lt_i32_e32 vcc, s60, v34
	v_cvt_pk_bf16_f32 v55, v56, v57
	global_store_dwordx2 v[64:65], v[54:55], off offset:-1024
	v_pk_mul_f32 v[54:55], v[52:53], v[116:117] op_sel_hi:[0,1]
	v_pk_mul_f32 v[56:57], v[52:53], v[118:119] op_sel_hi:[0,1]
	v_pk_fma_f32 v[54:55], v[18:19], v[54:55], v[22:23]
	v_pk_mul_f32 v[48:49], v[52:53], v[48:49] op_sel_hi:[0,1]
	v_pk_fma_f32 v[50:51], v[30:31], v[50:51], v[26:27]
	s_or_b64 s[30:31], vcc, s[30:31]
	v_pk_fma_f32 v[56:57], v[20:21], v[56:57], v[24:25]
	v_cvt_pk_bf16_f32 v54, v54, v55
	v_pk_fma_f32 v[48:49], v[32:33], v[48:49], v[28:29]
	v_cvt_pk_bf16_f32 v55, v56, v57
	global_store_dwordx2 v[64:65], v[54:55], off offset:-512
	v_cvt_pk_bf16_f32 v50, v50, v51
	v_cvt_pk_bf16_f32 v51, v48, v49
	global_store_dwordx2 v[64:65], v[50:51], off
	s_andn2_b64 exec, exec, s[30:31]
	s_cbranch_execz .LBB0_702
.LBB0_700:
	v_add_u32_e32 v35, 0xffffe000, v34
	v_lshrrev_b32_e32 v35, 11, v35
	s_movk_i32 s5, 0x1fff
	v_add_u32_e32 v35, 1, v35
	v_cmp_lt_i32_e32 vcc, s5, v34
	s_nop 1
	v_cndmask_b32_e32 v35, 0, v35, vcc
	global_load_dwordx2 v[48:49], v[38:39], off offset:-2048 nt
	global_load_dwordx2 v[60:61], v[38:39], off nt
	global_load_dwordx2 v[66:67], v[38:39], off offset:-4096 nt
	v_add_co_u32_e32 v50, vcc, 0xfffff000, v38
	s_nop 1
	v_addc_co_u32_e32 v51, vcc, -1, v39, vcc
	global_load_dwordx2 v[68:69], v[50:51], off offset:-2048 nt
	global_load_dwordx2 v[70:71], v[50:51], off offset:-3584 nt
	global_load_dwordx2 v[72:73], v[50:51], off offset:-3072 nt
	global_load_dwordx2 v[86:87], v[50:51], off offset:-2560 nt
	global_load_dwordx2 v[92:93], v[50:51], off offset:-1536 nt
	global_load_dwordx2 v[94:95], v[50:51], off offset:-1024 nt
	global_load_dwordx2 v[96:97], v[50:51], off offset:-512 nt
	global_load_dwordx2 v[90:91], v[38:39], off offset:-3584 nt
	global_load_dwordx2 v[88:89], v[38:39], off offset:-3072 nt
	global_load_dwordx2 v[84:85], v[38:39], off offset:-2560 nt
	global_load_dwordx2 v[82:83], v[38:39], off offset:-1536 nt
	global_load_dwordx2 v[80:81], v[38:39], off offset:-1024 nt
	global_load_dwordx2 v[118:119], v[38:39], off offset:-512 nt
	v_cmp_ne_u32_e32 vcc, v35, v0
	s_and_saveexec_b64 s[34:35], vcc
	s_cbranch_execz .LBB0_699
	v_mul_u32_u24_e32 v0, 0x1800, v35
	v_lshl_add_u64 v[156:157], v[0:1], 2, s[18:19]
	s_mov_b64 s[10:11], 0x1000
	v_lshl_add_u64 v[158:159], v[156:157], 0, s[10:11]
	v_mov_b32_e32 v41, v1
	v_mov_b32_e32 v43, v1
	v_mov_b32_e32 v45, v1
	v_mov_b32_e32 v47, v1
	v_lshl_add_u64 v[52:53], v[156:157], 0, v[40:41]
	v_lshl_add_u64 v[160:161], v[158:159], 0, v[40:41]
	v_lshl_add_u64 v[162:163], v[158:159], 0, v[42:43]
	v_lshl_add_u64 v[164:165], v[158:159], 0, v[44:45]
	v_lshl_add_u64 v[166:167], v[158:159], 0, v[46:47]
	global_load_dwordx4 v[140:143], v[160:161], off
	global_load_dwordx4 v[144:147], v[162:163], off
	global_load_dwordx4 v[148:151], v[164:165], off
	global_load_dwordx4 v[152:155], v[166:167], off
	global_load_dwordx4 v[2:5], v[36:37], off
	global_load_dwordx4 v[10:13], v[36:37], off offset:1024
	global_load_dwordx4 v[18:21], v[36:37], off offset:2048
	global_load_dwordx4 v[30:33], v[36:37], off offset:3072
	global_load_dwordx4 v[6:9], v[52:53], off
	global_load_dwordx4 v[14:17], v[52:53], off offset:1024
	global_load_dwordx4 v[22:25], v[52:53], off offset:2048
	global_load_dwordx4 v[26:29], v[52:53], off offset:3072
	v_mov_b32_e32 v0, v35
	s_waitcnt vmcnt(0)
	v_pk_add_f32 v[142:143], v[142:143], 1.0 op_sel_hi:[1,0]
	v_pk_add_f32 v[140:141], v[140:141], 1.0 op_sel_hi:[1,0]
	v_pk_mul_f32 v[4:5], v[4:5], v[142:143]
	v_pk_mul_f32 v[2:3], v[2:3], v[140:141]
	v_pk_add_f32 v[146:147], v[146:147], 1.0 op_sel_hi:[1,0]
	v_pk_add_f32 v[144:145], v[144:145], 1.0 op_sel_hi:[1,0]
	v_pk_mul_f32 v[12:13], v[12:13], v[146:147]
	v_pk_mul_f32 v[10:11], v[10:11], v[144:145]
	v_pk_add_f32 v[150:151], v[150:151], 1.0 op_sel_hi:[1,0]
	v_pk_add_f32 v[148:149], v[148:149], 1.0 op_sel_hi:[1,0]
	v_pk_mul_f32 v[20:21], v[20:21], v[150:151]
	v_pk_mul_f32 v[18:19], v[18:19], v[148:149]
	v_pk_add_f32 v[154:155], v[154:155], 1.0 op_sel_hi:[1,0]
	v_pk_add_f32 v[152:153], v[152:153], 1.0 op_sel_hi:[1,0]
	v_pk_mul_f32 v[32:33], v[32:33], v[154:155]
	v_pk_mul_f32 v[30:31], v[30:31], v[152:153]
	s_branch .LBB0_699
